# peeled first K iteration (inline-0 srcC) now on all 8 GEMM loops incl. the one-shot out-proj/down GEMMs (zeroing sat after the prologue wait)
# speedup vs baseline: 1.0046x; 1.0008x over previous
.LBB0_610:
	v_bfe_u32 v133, v226, 4, 2
	s_lshl_b32 s6, s6, 5
	v_lshlrev_b32_e32 v11, 6, v226
	v_and_b32_e32 v193, 15, v226
	v_lshlrev_b32_e32 v9, 4, v133
	s_and_b32 s14, s6, 0x60
	v_and_b32_e32 v200, 0x3c0, v11
	v_lshl_or_b32 v132, s7, 6, v193
	v_lshl_or_b32 v194, v193, 6, v9
	s_lshl_b32 s7, s7, 13
	v_and_b32_e32 v199, 32, v125
	v_or_b32_e32 v11, v9, v200
	s_lshl_b32 s6, s14, 7
	v_bitop3_b32 v10, v194, s7, v199 bitop3:0xde
	v_bitop3_b32 v196, v9, v199, v200 bitop3:0x36
	v_bitop3_b32 v9, s6, v11, v199 bitop3:0xf6
	s_mov_b64 s[6:7], 0x80
	s_add_i32 m0, s16, 0x18000
	v_lshl_add_u64 v[6:7], v[6:7], 0, s[6:7]
	s_waitcnt vmcnt(2)
	s_barrier
	global_load_lds_dwordx4 v[6:7], off
	v_lshl_add_u64 v[4:5], v[4:5], 0, s[6:7]
	s_add_i32 m0, s16, 0x1a000
	s_add_i32 s20, s16, 0x8000
	s_add_i32 s21, s16, 0xa000
	global_load_lds_dwordx4 v[4:5], off
	v_lshl_add_u64 v[2:3], v[2:3], 0, s[6:7]
	s_mov_b32 m0, s20
	s_add_u32 s22, s2, 0x40080
	global_load_lds_dwordx4 v[2:3], off
	v_lshl_add_u64 v[0:1], v[0:1], 0, s[6:7]
	s_mov_b32 m0, s21
	s_addc_u32 s23, s3, 0
	global_load_lds_dwordx4 v[0:1], off
	s_add_i32 m0, s16, 0x1c000
	v_lshl_add_u64 v[0:1], s[22:23], 0, v[156:157]
	global_load_lds_dwordx4 v[0:1], off
	v_lshl_add_u64 v[0:1], s[22:23], 0, v[152:153]
	s_add_i32 m0, s16, 0x1e000
	v_lshrrev_b32_e32 v195, 7, v226
	global_load_lds_dwordx4 v[0:1], off
	v_lshlrev_b32_e32 v0, 15, v195
	v_lshlrev_b32_e32 v1, 11, v186
	v_readlane_b32 s48, v254, 0
	v_or3_b32 v0, v184, v0, v1
	v_readlane_b32 s50, v254, 2
	v_lshrrev_b32_e32 v197, 11, v8
	v_add_u32_e32 v160, v0, v185
	v_readlane_b32 s51, v254, 3
	s_add_u32 s10, s50, s10
	v_lshlrev_b32_e32 v0, 15, v197
	s_waitcnt vmcnt(6)
	s_addc_u32 s11, s51, s11
	v_or3_b32 v0, v184, v0, v1
	s_add_i32 s36, 0, 0x10000
	s_add_i32 s37, 0, 0x14000
	s_add_i32 s45, 0, 0x18000
	s_add_i32 s46, 0, 0x1c000
	v_mov_b32_e32 v161, v157
	v_add_u32_e32 v162, v0, v185
	v_mov_b32_e32 v163, v157
	s_add_i32 s30, s36, s12
	s_add_i32 s33, s37, s12
	s_add_i32 s35, s45, s12
	s_add_i32 s47, s46, s12
	s_mov_b64 s[8:9], 0x40080
	v_lshl_add_u64 v[128:129], s[10:11], 0, v[160:161]
	v_lshl_add_u64 v[130:131], s[10:11], 0, v[162:163]
	s_mov_b32 s22, -2
	v_add_u32_e32 v134, s36, v9
	v_add_u32_e32 v135, s37, v9
	v_add_u32_e32 v136, 0, v10
	s_add_i32 s23, s16, 0xc000
	s_add_i32 s29, s16, 0xe000
	s_add_i32 s31, s30, 0x2000
	s_add_i32 s34, s33, 0x2000
	v_add_u32_e32 v137, s45, v9
	v_add_u32_e32 v138, s46, v9
	s_add_i32 s41, s35, 0x2000
	s_add_i32 s48, s47, 0x2000
	s_barrier
	v_readlane_b32 s49, v254, 1
	ds_read_b128 v[140:143], v134
	ds_read_b128 v[144:147], v134 offset:1024
	ds_read_b128 v[148:151], v134 offset:2048
	ds_read_b128 v[164:167], v134 offset:3072
	ds_read_b128 v[168:171], v135
	ds_read_b128 v[172:175], v135 offset:1024
	ds_read_b128 v[176:179], v135 offset:2048
	ds_read_b128 v[206:209], v135 offset:3072
	s_add_u32 s10, s8, 0xfffc0080
	s_addc_u32 s11, s9, -1
	s_cmp_lg_u32 s22, 12
	s_cselect_b32 s10, s10, 0
	s_cselect_b32 s11, s11, 0
	s_add_u32 s12, s4, s10
	s_addc_u32 s13, s5, s11
	s_add_u32 s10, s2, s10
	s_addc_u32 s11, s3, s11
	s_mov_b32 m0, s23
	v_lshl_add_u64 v[180:181], v[128:129], 0, s[8:9]
	ds_read_b128 v[210:213], v136
	ds_read_b128 v[214:217], v136 offset:1024
	ds_read_b128 v[218:221], v136 offset:2048
	ds_read_b128 v[222:225], v136 offset:3072
	ds_read_b128 v[232:235], v136 offset:4096
	ds_read_b128 v[236:239], v136 offset:5120
	ds_read_b128 v[240:243], v136 offset:6144
	ds_read_b128 v[244:247], v136 offset:7168
	global_load_lds_dwordx4 v[180:181], off
	v_lshl_add_u64 v[180:181], v[130:131], 0, s[8:9]
	s_mov_b32 m0, s29
	s_nop 0
	global_load_lds_dwordx4 v[180:181], off
	s_waitcnt vmcnt(8)
	s_waitcnt lgkmcnt(0)
	s_barrier
	s_setprio 1
	s_waitcnt lgkmcnt(0)
	v_mfma_f32_16x16x32_bf16 v[124:127], v[140:143], v[210:213], 0
	v_mfma_f32_16x16x32_bf16 v[120:123], v[148:151], v[210:213], 0
	v_mfma_f32_16x16x32_bf16 v[108:111], v[140:143], v[218:221], 0
	v_mfma_f32_16x16x32_bf16 v[104:107], v[148:151], v[218:221], 0
	v_mfma_f32_16x16x32_bf16 v[92:95], v[140:143], v[232:235], 0
	v_mfma_f32_16x16x32_bf16 v[88:91], v[148:151], v[232:235], 0
	v_mfma_f32_16x16x32_bf16 v[76:79], v[140:143], v[240:243], 0
	v_mfma_f32_16x16x32_bf16 v[72:75], v[148:151], v[240:243], 0
	v_mfma_f32_16x16x32_bf16 v[124:127], v[144:147], v[214:217], v[124:127]
	v_mfma_f32_16x16x32_bf16 v[120:123], v[164:167], v[214:217], v[120:123]
	v_mfma_f32_16x16x32_bf16 v[108:111], v[144:147], v[222:225], v[108:111]
	v_mfma_f32_16x16x32_bf16 v[104:107], v[164:167], v[222:225], v[104:107]
	v_mfma_f32_16x16x32_bf16 v[92:95], v[144:147], v[236:239], v[92:95]
	v_mfma_f32_16x16x32_bf16 v[88:91], v[164:167], v[236:239], v[88:91]
	v_mfma_f32_16x16x32_bf16 v[76:79], v[144:147], v[244:247], v[76:79]
	v_mfma_f32_16x16x32_bf16 v[72:75], v[164:167], v[244:247], v[72:75]
	s_setprio 0
	s_setprio 1
	v_mfma_f32_16x16x32_bf16 v[116:119], v[168:171], v[210:213], 0
	v_mfma_f32_16x16x32_bf16 v[112:115], v[176:179], v[210:213], 0
	v_mfma_f32_16x16x32_bf16 v[100:103], v[168:171], v[218:221], 0
	v_mfma_f32_16x16x32_bf16 v[96:99], v[176:179], v[218:221], 0
	v_mfma_f32_16x16x32_bf16 v[84:87], v[168:171], v[232:235], 0
	v_mfma_f32_16x16x32_bf16 v[80:83], v[176:179], v[232:235], 0
	v_mfma_f32_16x16x32_bf16 v[68:71], v[168:171], v[240:243], 0
	v_mfma_f32_16x16x32_bf16 v[64:67], v[176:179], v[240:243], 0
	v_mfma_f32_16x16x32_bf16 v[116:119], v[172:175], v[214:217], v[116:119]
	v_mfma_f32_16x16x32_bf16 v[112:115], v[206:209], v[214:217], v[112:115]
	v_mfma_f32_16x16x32_bf16 v[100:103], v[172:175], v[222:225], v[100:103]
	v_mfma_f32_16x16x32_bf16 v[96:99], v[206:209], v[222:225], v[96:99]
	v_mfma_f32_16x16x32_bf16 v[84:87], v[172:175], v[236:239], v[84:87]
	v_mfma_f32_16x16x32_bf16 v[80:83], v[206:209], v[236:239], v[80:83]
	v_mfma_f32_16x16x32_bf16 v[68:71], v[172:175], v[244:247], v[68:71]
	v_mfma_f32_16x16x32_bf16 v[64:67], v[206:209], v[244:247], v[64:67]
	s_setprio 0
	s_barrier
	s_mov_b32 m0, s30
	v_lshl_add_u64 v[180:181], s[10:11], 0, v[156:157]
	s_add_u32 s50, s10, 0x40000
	ds_read_b128 v[210:213], v136 offset:16384
	ds_read_b128 v[214:217], v136 offset:17408
	ds_read_b128 v[218:221], v136 offset:18432
	ds_read_b128 v[222:225], v136 offset:19456
	ds_read_b128 v[232:235], v136 offset:20480
	ds_read_b128 v[236:239], v136 offset:21504
	ds_read_b128 v[240:243], v136 offset:22528
	ds_read_b128 v[244:247], v136 offset:23552
	global_load_lds_dwordx4 v[180:181], off
	v_lshl_add_u64 v[202:203], s[10:11], 0, v[152:153]
	s_mov_b32 m0, s31
	s_addc_u32 s51, s11, 0
	global_load_lds_dwordx4 v[202:203], off
	v_lshl_add_u64 v[248:249], s[50:51], 0, v[156:157]
	s_mov_b32 m0, s33
	v_lshl_add_u64 v[250:251], s[12:13], 0, v[154:155]
	global_load_lds_dwordx4 v[248:249], off
	v_lshl_add_u64 v[248:249], s[50:51], 0, v[152:153]
	s_mov_b32 m0, s34
	s_nop 0
	global_load_lds_dwordx4 v[248:249], off
	v_lshl_add_u64 v[248:249], s[12:13], 0, v[158:159]
	s_mov_b32 m0, s16
	s_nop 0
	global_load_lds_dwordx4 v[248:249], off
	s_mov_b32 m0, s17
	s_nop 0
	global_load_lds_dwordx4 v[250:251], off
	s_waitcnt vmcnt(8)
	s_waitcnt lgkmcnt(0)
	s_barrier
	s_setprio 1
	s_waitcnt lgkmcnt(0)
	v_mfma_f32_16x16x32_bf16 v[60:63], v[140:143], v[210:213], 0
	v_mfma_f32_16x16x32_bf16 v[56:59], v[148:151], v[210:213], 0
	v_mfma_f32_16x16x32_bf16 v[44:47], v[140:143], v[218:221], 0
	v_mfma_f32_16x16x32_bf16 v[40:43], v[148:151], v[218:221], 0
	v_mfma_f32_16x16x32_bf16 v[28:31], v[140:143], v[232:235], 0
	v_mfma_f32_16x16x32_bf16 v[24:27], v[148:151], v[232:235], 0
	v_mfma_f32_16x16x32_bf16 v[12:15], v[140:143], v[240:243], 0
	v_mfma_f32_16x16x32_bf16 v[8:11], v[148:151], v[240:243], 0
	v_mfma_f32_16x16x32_bf16 v[60:63], v[144:147], v[214:217], v[60:63]
	v_mfma_f32_16x16x32_bf16 v[56:59], v[164:167], v[214:217], v[56:59]
	v_mfma_f32_16x16x32_bf16 v[44:47], v[144:147], v[222:225], v[44:47]
	v_mfma_f32_16x16x32_bf16 v[40:43], v[164:167], v[222:225], v[40:43]
	v_mfma_f32_16x16x32_bf16 v[28:31], v[144:147], v[236:239], v[28:31]
	v_mfma_f32_16x16x32_bf16 v[24:27], v[164:167], v[236:239], v[24:27]
	v_mfma_f32_16x16x32_bf16 v[12:15], v[144:147], v[244:247], v[12:15]
	v_mfma_f32_16x16x32_bf16 v[8:11], v[164:167], v[244:247], v[8:11]
	s_setprio 0
	s_setprio 1
	v_mfma_f32_16x16x32_bf16 v[52:55], v[168:171], v[210:213], 0
	v_mfma_f32_16x16x32_bf16 v[48:51], v[176:179], v[210:213], 0
	v_mfma_f32_16x16x32_bf16 v[36:39], v[168:171], v[218:221], 0
	v_mfma_f32_16x16x32_bf16 v[32:35], v[176:179], v[218:221], 0
	v_mfma_f32_16x16x32_bf16 v[20:23], v[168:171], v[232:235], 0
	v_mfma_f32_16x16x32_bf16 v[16:19], v[176:179], v[232:235], 0
	v_mfma_f32_16x16x32_bf16 v[4:7], v[168:171], v[240:243], 0
	v_mfma_f32_16x16x32_bf16 v[0:3], v[176:179], v[240:243], 0
	v_mfma_f32_16x16x32_bf16 v[52:55], v[172:175], v[214:217], v[52:55]
	v_mfma_f32_16x16x32_bf16 v[48:51], v[206:209], v[214:217], v[48:51]
	v_mfma_f32_16x16x32_bf16 v[36:39], v[172:175], v[222:225], v[36:39]
	v_mfma_f32_16x16x32_bf16 v[32:35], v[206:209], v[222:225], v[32:35]
	v_mfma_f32_16x16x32_bf16 v[20:23], v[172:175], v[236:239], v[20:23]
	v_mfma_f32_16x16x32_bf16 v[16:19], v[206:209], v[236:239], v[16:19]
	v_mfma_f32_16x16x32_bf16 v[4:7], v[172:175], v[244:247], v[4:7]
	v_mfma_f32_16x16x32_bf16 v[0:3], v[206:209], v[244:247], v[0:3]
	s_setprio 0
	s_barrier
	ds_read_b128 v[140:143], v137
	ds_read_b128 v[144:147], v137 offset:1024
	ds_read_b128 v[148:151], v137 offset:2048
	ds_read_b128 v[164:167], v137 offset:3072
	ds_read_b128 v[168:171], v138
	ds_read_b128 v[172:175], v138 offset:1024
	ds_read_b128 v[176:179], v138 offset:2048
	ds_read_b128 v[206:209], v138 offset:3072
	s_add_u32 s12, s12, 0x40000
	s_addc_u32 s13, s13, 0
	s_mov_b32 m0, s18
	v_lshl_add_u64 v[252:253], s[12:13], 0, v[158:159]
	ds_read_b128 v[210:213], v136 offset:32768
	ds_read_b128 v[214:217], v136 offset:33792
	ds_read_b128 v[218:221], v136 offset:34816
	ds_read_b128 v[222:225], v136 offset:35840
	ds_read_b128 v[232:235], v136 offset:36864
	ds_read_b128 v[236:239], v136 offset:37888
	ds_read_b128 v[240:243], v136 offset:38912
	ds_read_b128 v[244:247], v136 offset:39936
	global_load_lds_dwordx4 v[252:253], off
	v_lshl_add_u64 v[252:253], s[12:13], 0, v[154:155]
	s_mov_b32 m0, s19
	s_nop 0
	global_load_lds_dwordx4 v[252:253], off
	s_waitcnt vmcnt(8)
	s_waitcnt lgkmcnt(0)
	s_barrier
	s_setprio 1
	s_waitcnt lgkmcnt(0)
	v_mfma_f32_16x16x32_bf16 v[124:127], v[140:143], v[210:213], v[124:127]
	v_mfma_f32_16x16x32_bf16 v[120:123], v[148:151], v[210:213], v[120:123]
	v_mfma_f32_16x16x32_bf16 v[108:111], v[140:143], v[218:221], v[108:111]
	v_mfma_f32_16x16x32_bf16 v[104:107], v[148:151], v[218:221], v[104:107]
	v_mfma_f32_16x16x32_bf16 v[92:95], v[140:143], v[232:235], v[92:95]
	v_mfma_f32_16x16x32_bf16 v[88:91], v[148:151], v[232:235], v[88:91]
	v_mfma_f32_16x16x32_bf16 v[76:79], v[140:143], v[240:243], v[76:79]
	v_mfma_f32_16x16x32_bf16 v[72:75], v[148:151], v[240:243], v[72:75]
	v_mfma_f32_16x16x32_bf16 v[124:127], v[144:147], v[214:217], v[124:127]
	v_mfma_f32_16x16x32_bf16 v[120:123], v[164:167], v[214:217], v[120:123]
	v_mfma_f32_16x16x32_bf16 v[108:111], v[144:147], v[222:225], v[108:111]
	v_mfma_f32_16x16x32_bf16 v[104:107], v[164:167], v[222:225], v[104:107]
	v_mfma_f32_16x16x32_bf16 v[92:95], v[144:147], v[236:239], v[92:95]
	v_mfma_f32_16x16x32_bf16 v[88:91], v[164:167], v[236:239], v[88:91]
	v_mfma_f32_16x16x32_bf16 v[76:79], v[144:147], v[244:247], v[76:79]
	v_mfma_f32_16x16x32_bf16 v[72:75], v[164:167], v[244:247], v[72:75]
	s_setprio 0
	s_setprio 1
	v_mfma_f32_16x16x32_bf16 v[116:119], v[168:171], v[210:213], v[116:119]
	v_mfma_f32_16x16x32_bf16 v[112:115], v[176:179], v[210:213], v[112:115]
	v_mfma_f32_16x16x32_bf16 v[100:103], v[168:171], v[218:221], v[100:103]
	v_mfma_f32_16x16x32_bf16 v[96:99], v[176:179], v[218:221], v[96:99]
	v_mfma_f32_16x16x32_bf16 v[84:87], v[168:171], v[232:235], v[84:87]
	v_mfma_f32_16x16x32_bf16 v[80:83], v[176:179], v[232:235], v[80:83]
	v_mfma_f32_16x16x32_bf16 v[68:71], v[168:171], v[240:243], v[68:71]
	v_mfma_f32_16x16x32_bf16 v[64:67], v[176:179], v[240:243], v[64:67]
	v_mfma_f32_16x16x32_bf16 v[116:119], v[172:175], v[214:217], v[116:119]
	v_mfma_f32_16x16x32_bf16 v[112:115], v[206:209], v[214:217], v[112:115]
	v_mfma_f32_16x16x32_bf16 v[100:103], v[172:175], v[222:225], v[100:103]
	v_mfma_f32_16x16x32_bf16 v[96:99], v[206:209], v[222:225], v[96:99]
	v_mfma_f32_16x16x32_bf16 v[84:87], v[172:175], v[236:239], v[84:87]
	v_mfma_f32_16x16x32_bf16 v[80:83], v[206:209], v[236:239], v[80:83]
	v_mfma_f32_16x16x32_bf16 v[68:71], v[172:175], v[244:247], v[68:71]
	v_mfma_f32_16x16x32_bf16 v[64:67], v[206:209], v[244:247], v[64:67]
	s_setprio 0
	s_barrier
	s_mov_b32 m0, s35
	v_lshl_add_u64 v[180:181], v[180:181], 0, s[6:7]
	s_add_u32 s10, s10, 0x40080
	ds_read_b128 v[210:213], v136 offset:49152
	ds_read_b128 v[214:217], v136 offset:50176
	ds_read_b128 v[218:221], v136 offset:51200
	ds_read_b128 v[222:225], v136 offset:52224
	ds_read_b128 v[232:235], v136 offset:53248
	ds_read_b128 v[236:239], v136 offset:54272
	ds_read_b128 v[240:243], v136 offset:55296
	ds_read_b128 v[244:247], v136 offset:56320
	global_load_lds_dwordx4 v[180:181], off
	v_lshl_add_u64 v[180:181], v[202:203], 0, s[6:7]
	s_mov_b32 m0, s41
	s_addc_u32 s11, s11, 0
	global_load_lds_dwordx4 v[180:181], off
	v_lshl_add_u64 v[180:181], s[10:11], 0, v[156:157]
	s_mov_b32 m0, s47
	s_nop 0
	global_load_lds_dwordx4 v[180:181], off
	v_lshl_add_u64 v[180:181], s[10:11], 0, v[152:153]
	s_mov_b32 m0, s48
	s_nop 0
	global_load_lds_dwordx4 v[180:181], off
	v_lshl_add_u64 v[180:181], v[248:249], 0, s[6:7]
	s_mov_b32 m0, s20
	s_nop 0
	global_load_lds_dwordx4 v[180:181], off
	v_lshl_add_u64 v[180:181], v[250:251], 0, s[6:7]
	s_mov_b32 m0, s21
	s_nop 0
	global_load_lds_dwordx4 v[180:181], off
	s_waitcnt vmcnt(8)
	s_waitcnt lgkmcnt(0)
	s_barrier
	s_setprio 1
	s_waitcnt lgkmcnt(0)
	v_mfma_f32_16x16x32_bf16 v[60:63], v[140:143], v[210:213], v[60:63]
	v_mfma_f32_16x16x32_bf16 v[56:59], v[148:151], v[210:213], v[56:59]
	v_mfma_f32_16x16x32_bf16 v[44:47], v[140:143], v[218:221], v[44:47]
	v_mfma_f32_16x16x32_bf16 v[40:43], v[148:151], v[218:221], v[40:43]
	v_mfma_f32_16x16x32_bf16 v[28:31], v[140:143], v[232:235], v[28:31]
	v_mfma_f32_16x16x32_bf16 v[24:27], v[148:151], v[232:235], v[24:27]
	v_mfma_f32_16x16x32_bf16 v[12:15], v[140:143], v[240:243], v[12:15]
	v_mfma_f32_16x16x32_bf16 v[8:11], v[148:151], v[240:243], v[8:11]
	v_mfma_f32_16x16x32_bf16 v[60:63], v[144:147], v[214:217], v[60:63]
	v_mfma_f32_16x16x32_bf16 v[56:59], v[164:167], v[214:217], v[56:59]
	v_mfma_f32_16x16x32_bf16 v[44:47], v[144:147], v[222:225], v[44:47]
	v_mfma_f32_16x16x32_bf16 v[40:43], v[164:167], v[222:225], v[40:43]
	v_mfma_f32_16x16x32_bf16 v[28:31], v[144:147], v[236:239], v[28:31]
	v_mfma_f32_16x16x32_bf16 v[24:27], v[164:167], v[236:239], v[24:27]
	v_mfma_f32_16x16x32_bf16 v[12:15], v[144:147], v[244:247], v[12:15]
	v_mfma_f32_16x16x32_bf16 v[8:11], v[164:167], v[244:247], v[8:11]
	s_setprio 0
	s_setprio 1
	v_mfma_f32_16x16x32_bf16 v[52:55], v[168:171], v[210:213], v[52:55]
	v_mfma_f32_16x16x32_bf16 v[48:51], v[176:179], v[210:213], v[48:51]
	v_mfma_f32_16x16x32_bf16 v[36:39], v[168:171], v[218:221], v[36:39]
	v_mfma_f32_16x16x32_bf16 v[32:35], v[176:179], v[218:221], v[32:35]
	v_mfma_f32_16x16x32_bf16 v[20:23], v[168:171], v[232:235], v[20:23]
	v_mfma_f32_16x16x32_bf16 v[16:19], v[176:179], v[232:235], v[16:19]
	v_mfma_f32_16x16x32_bf16 v[4:7], v[168:171], v[240:243], v[4:7]
	v_mfma_f32_16x16x32_bf16 v[0:3], v[176:179], v[240:243], v[0:3]
	v_mfma_f32_16x16x32_bf16 v[52:55], v[172:175], v[214:217], v[52:55]
	v_mfma_f32_16x16x32_bf16 v[48:51], v[206:209], v[214:217], v[48:51]
	v_mfma_f32_16x16x32_bf16 v[36:39], v[172:175], v[222:225], v[36:39]
	v_mfma_f32_16x16x32_bf16 v[32:35], v[206:209], v[222:225], v[32:35]
	v_mfma_f32_16x16x32_bf16 v[20:23], v[172:175], v[236:239], v[20:23]
	v_mfma_f32_16x16x32_bf16 v[16:19], v[206:209], v[236:239], v[16:19]
	v_mfma_f32_16x16x32_bf16 v[4:7], v[172:175], v[244:247], v[4:7]
	v_mfma_f32_16x16x32_bf16 v[0:3], v[206:209], v[244:247], v[0:3]
	s_setprio 0
	s_barrier
	s_add_i32 s22, s22, 2
	s_add_u32 s8, s8, 0x100
	s_addc_u32 s9, s9, 0
	s_cmp_gt_u32 s22, 13

.LBB0_683:
	v_lshl_or_b32 v140, s7, 6, v193
	s_lshl_b32 s7, s7, 13
	s_lshl_b32 s6, s6, 5
	v_bitop3_b32 v8, v194, s7, v138 bitop3:0xde
	s_and_b32 s23, s6, 0x60
	s_mov_b64 s[6:7], 0x80
	s_add_i32 m0, s19, 0x18000
	v_lshl_add_u64 v[6:7], v[6:7], 0, s[6:7]
	s_waitcnt vmcnt(2)
	s_barrier
	global_load_lds_dwordx4 v[6:7], off
	v_lshl_add_u64 v[4:5], v[4:5], 0, s[6:7]
	s_add_i32 m0, s19, 0x1a000
	s_add_i32 s28, s19, 0x8000
	s_add_i32 s29, s19, 0xa000
	global_load_lds_dwordx4 v[4:5], off
	v_lshl_add_u64 v[2:3], v[2:3], 0, s[6:7]
	s_mov_b32 m0, s28
	s_add_u32 s14, s0, 0x100080
	global_load_lds_dwordx4 v[2:3], off
	v_lshl_add_u64 v[0:1], v[0:1], 0, s[6:7]
	s_mov_b32 m0, s29
	s_addc_u32 s15, s1, 0
	global_load_lds_dwordx4 v[0:1], off
	s_add_i32 m0, s19, 0x1c000
	v_lshl_add_u64 v[0:1], s[14:15], 0, v[132:133]
	global_load_lds_dwordx4 v[0:1], off
	v_lshl_add_u64 v[0:1], s[14:15], 0, v[128:129]
	s_add_i32 m0, s19, 0x1e000
	s_add_i32 s12, s44, s53
	global_load_lds_dwordx4 v[0:1], off
	s_lshl_b64 s[12:13], s[12:13], 21
	v_lshlrev_b32_e32 v0, 17, v195
	v_lshlrev_b32_e32 v2, 13, v186
	v_or3_b32 v0, v184, v0, v2
	s_add_u32 s12, s96, s12
	v_add_u32_e32 v0, v0, v185
	v_mov_b32_e32 v1, v133
	s_addc_u32 s13, s97, s13
	v_lshl_add_u64 v[136:137], s[12:13], 0, v[0:1]
	v_lshlrev_b32_e32 v0, 17, v197
	v_lshl_or_b32 v9, s23, 7, v196
	s_waitcnt vmcnt(6)
	v_or3_b32 v0, v184, v0, v2
	v_add_u32_e32 v0, v0, v185
	v_add_u32_e32 v141, s36, v9
	s_add_i32 s34, s36, s16
	s_add_i32 s36, s37, s16
	v_add_u32_e32 v144, s45, v9
	s_add_i32 s41, s45, s16
	s_add_i32 s45, s46, s16
	v_lshl_add_u64 v[138:139], s[12:13], 0, v[0:1]
	s_mov_b32 s30, -2
	s_mov_b64 s[12:13], 0x7600080
	v_add_u32_e32 v142, s37, v9
	v_add_u32_e32 v143, 0, v8
	s_add_i32 s31, s19, 0xc000
	s_add_i32 s33, s19, 0xe000
	s_add_i32 s35, s34, 0x2000
	s_add_i32 s37, s36, 0x2000
	v_add_u32_e32 v145, s46, v9
	s_add_i32 s44, s41, 0x2000
	s_add_i32 s46, s45, 0x2000
	s_barrier
	ds_read_b128 v[146:149], v141
	ds_read_b128 v[150:153], v141 offset:1024
	ds_read_b128 v[154:157], v141 offset:2048
	ds_read_b128 v[158:161], v141 offset:3072
	ds_read_b128 v[162:165], v142
	ds_read_b128 v[166:169], v142 offset:1024
	ds_read_b128 v[170:173], v142 offset:2048
	ds_read_b128 v[174:177], v142 offset:3072
	s_add_u32 s14, s12, 0xf8a00080
	s_addc_u32 s15, s13, -1
	s_cmp_lg_u32 s30, 60
	s_cselect_b32 s14, s14, 0
	s_cselect_b32 s15, s15, 0
	s_add_u32 s16, s2, s14
	s_addc_u32 s17, s3, s15
	s_add_u32 s14, s0, s14
	s_addc_u32 s15, s1, s15
	s_mov_b32 m0, s31
	v_lshl_add_u64 v[218:219], v[136:137], 0, s[12:13]
	ds_read_b128 v[178:181], v143
	ds_read_b128 v[184:187], v143 offset:1024
	ds_read_b128 v[188:191], v143 offset:2048
	ds_read_b128 v[194:197], v143 offset:3072
	ds_read_b128 v[200:203], v143 offset:4096
	ds_read_b128 v[206:209], v143 offset:5120
	ds_read_b128 v[210:213], v143 offset:6144
	ds_read_b128 v[214:217], v143 offset:7168
	global_load_lds_dwordx4 v[218:219], off
	v_lshl_add_u64 v[218:219], v[138:139], 0, s[12:13]
	s_mov_b32 m0, s33
	s_nop 0
	global_load_lds_dwordx4 v[218:219], off
	s_waitcnt vmcnt(8)
	s_waitcnt lgkmcnt(0)
	s_barrier
	s_setprio 1
	s_waitcnt lgkmcnt(0)
	v_mfma_f32_16x16x32_bf16 v[124:127], v[146:149], v[178:181], 0
	v_mfma_f32_16x16x32_bf16 v[120:123], v[154:157], v[178:181], 0
	v_mfma_f32_16x16x32_bf16 v[108:111], v[146:149], v[188:191], 0
	v_mfma_f32_16x16x32_bf16 v[104:107], v[154:157], v[188:191], 0
	v_mfma_f32_16x16x32_bf16 v[92:95], v[146:149], v[200:203], 0
	v_mfma_f32_16x16x32_bf16 v[88:91], v[154:157], v[200:203], 0
	v_mfma_f32_16x16x32_bf16 v[76:79], v[146:149], v[210:213], 0
	v_mfma_f32_16x16x32_bf16 v[72:75], v[154:157], v[210:213], 0
	v_mfma_f32_16x16x32_bf16 v[124:127], v[150:153], v[184:187], v[124:127]
	v_mfma_f32_16x16x32_bf16 v[120:123], v[158:161], v[184:187], v[120:123]
	v_mfma_f32_16x16x32_bf16 v[108:111], v[150:153], v[194:197], v[108:111]
	v_mfma_f32_16x16x32_bf16 v[104:107], v[158:161], v[194:197], v[104:107]
	v_mfma_f32_16x16x32_bf16 v[92:95], v[150:153], v[206:209], v[92:95]
	v_mfma_f32_16x16x32_bf16 v[88:91], v[158:161], v[206:209], v[88:91]
	v_mfma_f32_16x16x32_bf16 v[76:79], v[150:153], v[214:217], v[76:79]
	v_mfma_f32_16x16x32_bf16 v[72:75], v[158:161], v[214:217], v[72:75]
	s_setprio 0
	s_setprio 1
	v_mfma_f32_16x16x32_bf16 v[116:119], v[162:165], v[178:181], 0
	v_mfma_f32_16x16x32_bf16 v[112:115], v[170:173], v[178:181], 0
	v_mfma_f32_16x16x32_bf16 v[100:103], v[162:165], v[188:191], 0
	v_mfma_f32_16x16x32_bf16 v[96:99], v[170:173], v[188:191], 0
	v_mfma_f32_16x16x32_bf16 v[84:87], v[162:165], v[200:203], 0
	v_mfma_f32_16x16x32_bf16 v[80:83], v[170:173], v[200:203], 0
	v_mfma_f32_16x16x32_bf16 v[68:71], v[162:165], v[210:213], 0
	v_mfma_f32_16x16x32_bf16 v[64:67], v[170:173], v[210:213], 0
	v_mfma_f32_16x16x32_bf16 v[116:119], v[166:169], v[184:187], v[116:119]
	v_mfma_f32_16x16x32_bf16 v[112:115], v[174:177], v[184:187], v[112:115]
	v_mfma_f32_16x16x32_bf16 v[100:103], v[166:169], v[194:197], v[100:103]
	v_mfma_f32_16x16x32_bf16 v[96:99], v[174:177], v[194:197], v[96:99]
	v_mfma_f32_16x16x32_bf16 v[84:87], v[166:169], v[206:209], v[84:87]
	v_mfma_f32_16x16x32_bf16 v[80:83], v[174:177], v[206:209], v[80:83]
	v_mfma_f32_16x16x32_bf16 v[68:71], v[166:169], v[214:217], v[68:71]
	v_mfma_f32_16x16x32_bf16 v[64:67], v[174:177], v[214:217], v[64:67]
	s_setprio 0
	s_barrier
	s_mov_b32 m0, s34
	v_lshl_add_u64 v[218:219], s[14:15], 0, v[132:133]
	s_add_u32 s48, s14, 0x100000
	ds_read_b128 v[178:181], v143 offset:16384
	ds_read_b128 v[184:187], v143 offset:17408
	ds_read_b128 v[188:191], v143 offset:18432
	ds_read_b128 v[194:197], v143 offset:19456
	ds_read_b128 v[200:203], v143 offset:20480
	ds_read_b128 v[206:209], v143 offset:21504
	ds_read_b128 v[210:213], v143 offset:22528
	ds_read_b128 v[214:217], v143 offset:23552
	global_load_lds_dwordx4 v[218:219], off
	v_lshl_add_u64 v[220:221], s[14:15], 0, v[128:129]
	s_mov_b32 m0, s35
	s_addc_u32 s49, s15, 0
	global_load_lds_dwordx4 v[220:221], off
	v_lshl_add_u64 v[222:223], s[48:49], 0, v[132:133]
	s_mov_b32 m0, s36
	v_lshl_add_u64 v[224:225], s[16:17], 0, v[130:131]
	global_load_lds_dwordx4 v[222:223], off
	v_lshl_add_u64 v[222:223], s[48:49], 0, v[128:129]
	s_mov_b32 m0, s37
	s_nop 0
	global_load_lds_dwordx4 v[222:223], off
	v_lshl_add_u64 v[222:223], s[16:17], 0, v[134:135]
	s_mov_b32 m0, s19
	s_nop 0
	global_load_lds_dwordx4 v[222:223], off
	s_mov_b32 m0, s20
	s_nop 0
	global_load_lds_dwordx4 v[224:225], off
	s_waitcnt vmcnt(8)
	s_waitcnt lgkmcnt(0)
	s_barrier
	s_setprio 1
	s_waitcnt lgkmcnt(0)
	v_mfma_f32_16x16x32_bf16 v[60:63], v[146:149], v[178:181], 0
	v_mfma_f32_16x16x32_bf16 v[56:59], v[154:157], v[178:181], 0
	v_mfma_f32_16x16x32_bf16 v[44:47], v[146:149], v[188:191], 0
	v_mfma_f32_16x16x32_bf16 v[40:43], v[154:157], v[188:191], 0
	v_mfma_f32_16x16x32_bf16 v[28:31], v[146:149], v[200:203], 0
	v_mfma_f32_16x16x32_bf16 v[24:27], v[154:157], v[200:203], 0
	v_mfma_f32_16x16x32_bf16 v[12:15], v[146:149], v[210:213], 0
	v_mfma_f32_16x16x32_bf16 v[8:11], v[154:157], v[210:213], 0
	v_mfma_f32_16x16x32_bf16 v[60:63], v[150:153], v[184:187], v[60:63]
	v_mfma_f32_16x16x32_bf16 v[56:59], v[158:161], v[184:187], v[56:59]
	v_mfma_f32_16x16x32_bf16 v[44:47], v[150:153], v[194:197], v[44:47]
	v_mfma_f32_16x16x32_bf16 v[40:43], v[158:161], v[194:197], v[40:43]
	v_mfma_f32_16x16x32_bf16 v[28:31], v[150:153], v[206:209], v[28:31]
	v_mfma_f32_16x16x32_bf16 v[24:27], v[158:161], v[206:209], v[24:27]
	v_mfma_f32_16x16x32_bf16 v[12:15], v[150:153], v[214:217], v[12:15]
	v_mfma_f32_16x16x32_bf16 v[8:11], v[158:161], v[214:217], v[8:11]
	s_setprio 0
	s_setprio 1
	v_mfma_f32_16x16x32_bf16 v[52:55], v[162:165], v[178:181], 0
	v_mfma_f32_16x16x32_bf16 v[48:51], v[170:173], v[178:181], 0
	v_mfma_f32_16x16x32_bf16 v[36:39], v[162:165], v[188:191], 0
	v_mfma_f32_16x16x32_bf16 v[32:35], v[170:173], v[188:191], 0
	v_mfma_f32_16x16x32_bf16 v[20:23], v[162:165], v[200:203], 0
	v_mfma_f32_16x16x32_bf16 v[16:19], v[170:173], v[200:203], 0
	v_mfma_f32_16x16x32_bf16 v[4:7], v[162:165], v[210:213], 0
	v_mfma_f32_16x16x32_bf16 v[0:3], v[170:173], v[210:213], 0
	v_mfma_f32_16x16x32_bf16 v[52:55], v[166:169], v[184:187], v[52:55]
	v_mfma_f32_16x16x32_bf16 v[48:51], v[174:177], v[184:187], v[48:51]
	v_mfma_f32_16x16x32_bf16 v[36:39], v[166:169], v[194:197], v[36:39]
	v_mfma_f32_16x16x32_bf16 v[32:35], v[174:177], v[194:197], v[32:35]
	v_mfma_f32_16x16x32_bf16 v[20:23], v[166:169], v[206:209], v[20:23]
	v_mfma_f32_16x16x32_bf16 v[16:19], v[174:177], v[206:209], v[16:19]
	v_mfma_f32_16x16x32_bf16 v[4:7], v[166:169], v[214:217], v[4:7]
	v_mfma_f32_16x16x32_bf16 v[0:3], v[174:177], v[214:217], v[0:3]
	s_setprio 0
	s_barrier
	ds_read_b128 v[146:149], v144
	ds_read_b128 v[150:153], v144 offset:1024
	ds_read_b128 v[154:157], v144 offset:2048
	ds_read_b128 v[158:161], v144 offset:3072
	ds_read_b128 v[162:165], v145
	ds_read_b128 v[166:169], v145 offset:1024
	ds_read_b128 v[170:173], v145 offset:2048
	ds_read_b128 v[174:177], v145 offset:3072
	s_add_u32 s16, s16, 0x100000
	s_addc_u32 s17, s17, 0
	s_mov_b32 m0, s21
	v_lshl_add_u64 v[232:233], s[16:17], 0, v[134:135]
	ds_read_b128 v[178:181], v143 offset:32768
	ds_read_b128 v[184:187], v143 offset:33792
	ds_read_b128 v[188:191], v143 offset:34816
	ds_read_b128 v[194:197], v143 offset:35840
	ds_read_b128 v[200:203], v143 offset:36864
	ds_read_b128 v[206:209], v143 offset:37888
	ds_read_b128 v[210:213], v143 offset:38912
	ds_read_b128 v[214:217], v143 offset:39936
	global_load_lds_dwordx4 v[232:233], off
	v_lshl_add_u64 v[232:233], s[16:17], 0, v[130:131]
	s_mov_b32 m0, s22
	s_nop 0
	global_load_lds_dwordx4 v[232:233], off
	s_waitcnt vmcnt(8)
	s_waitcnt lgkmcnt(0)
	s_barrier
	s_setprio 1
	s_waitcnt lgkmcnt(0)
	v_mfma_f32_16x16x32_bf16 v[124:127], v[146:149], v[178:181], v[124:127]
	v_mfma_f32_16x16x32_bf16 v[120:123], v[154:157], v[178:181], v[120:123]
	v_mfma_f32_16x16x32_bf16 v[108:111], v[146:149], v[188:191], v[108:111]
	v_mfma_f32_16x16x32_bf16 v[104:107], v[154:157], v[188:191], v[104:107]
	v_mfma_f32_16x16x32_bf16 v[92:95], v[146:149], v[200:203], v[92:95]
	v_mfma_f32_16x16x32_bf16 v[88:91], v[154:157], v[200:203], v[88:91]
	v_mfma_f32_16x16x32_bf16 v[76:79], v[146:149], v[210:213], v[76:79]
	v_mfma_f32_16x16x32_bf16 v[72:75], v[154:157], v[210:213], v[72:75]
	v_mfma_f32_16x16x32_bf16 v[124:127], v[150:153], v[184:187], v[124:127]
	v_mfma_f32_16x16x32_bf16 v[120:123], v[158:161], v[184:187], v[120:123]
	v_mfma_f32_16x16x32_bf16 v[108:111], v[150:153], v[194:197], v[108:111]
	v_mfma_f32_16x16x32_bf16 v[104:107], v[158:161], v[194:197], v[104:107]
	v_mfma_f32_16x16x32_bf16 v[92:95], v[150:153], v[206:209], v[92:95]
	v_mfma_f32_16x16x32_bf16 v[88:91], v[158:161], v[206:209], v[88:91]
	v_mfma_f32_16x16x32_bf16 v[76:79], v[150:153], v[214:217], v[76:79]
	v_mfma_f32_16x16x32_bf16 v[72:75], v[158:161], v[214:217], v[72:75]
	s_setprio 0
	s_setprio 1
	v_mfma_f32_16x16x32_bf16 v[116:119], v[162:165], v[178:181], v[116:119]
	v_mfma_f32_16x16x32_bf16 v[112:115], v[170:173], v[178:181], v[112:115]
	v_mfma_f32_16x16x32_bf16 v[100:103], v[162:165], v[188:191], v[100:103]
	v_mfma_f32_16x16x32_bf16 v[96:99], v[170:173], v[188:191], v[96:99]
	v_mfma_f32_16x16x32_bf16 v[84:87], v[162:165], v[200:203], v[84:87]
	v_mfma_f32_16x16x32_bf16 v[80:83], v[170:173], v[200:203], v[80:83]
	v_mfma_f32_16x16x32_bf16 v[68:71], v[162:165], v[210:213], v[68:71]
	v_mfma_f32_16x16x32_bf16 v[64:67], v[170:173], v[210:213], v[64:67]
	v_mfma_f32_16x16x32_bf16 v[116:119], v[166:169], v[184:187], v[116:119]
	v_mfma_f32_16x16x32_bf16 v[112:115], v[174:177], v[184:187], v[112:115]
	v_mfma_f32_16x16x32_bf16 v[100:103], v[166:169], v[194:197], v[100:103]
	v_mfma_f32_16x16x32_bf16 v[96:99], v[174:177], v[194:197], v[96:99]
	v_mfma_f32_16x16x32_bf16 v[84:87], v[166:169], v[206:209], v[84:87]
	v_mfma_f32_16x16x32_bf16 v[80:83], v[174:177], v[206:209], v[80:83]
	v_mfma_f32_16x16x32_bf16 v[68:71], v[166:169], v[214:217], v[68:71]
	v_mfma_f32_16x16x32_bf16 v[64:67], v[174:177], v[214:217], v[64:67]
	s_setprio 0
	s_barrier
	s_mov_b32 m0, s41
	v_lshl_add_u64 v[218:219], v[218:219], 0, s[6:7]
	s_add_u32 s14, s14, 0x100080
	ds_read_b128 v[178:181], v143 offset:49152
	ds_read_b128 v[184:187], v143 offset:50176
	ds_read_b128 v[188:191], v143 offset:51200
	ds_read_b128 v[194:197], v143 offset:52224
	ds_read_b128 v[200:203], v143 offset:53248
	ds_read_b128 v[206:209], v143 offset:54272
	ds_read_b128 v[210:213], v143 offset:55296
	ds_read_b128 v[214:217], v143 offset:56320
	global_load_lds_dwordx4 v[218:219], off
	v_lshl_add_u64 v[218:219], v[220:221], 0, s[6:7]
	s_mov_b32 m0, s44
	s_addc_u32 s15, s15, 0
	global_load_lds_dwordx4 v[218:219], off
	v_lshl_add_u64 v[218:219], s[14:15], 0, v[132:133]
	s_mov_b32 m0, s45
	s_nop 0
	global_load_lds_dwordx4 v[218:219], off
	v_lshl_add_u64 v[218:219], s[14:15], 0, v[128:129]
	s_mov_b32 m0, s46
	s_nop 0
	global_load_lds_dwordx4 v[218:219], off
	v_lshl_add_u64 v[218:219], v[222:223], 0, s[6:7]
	s_mov_b32 m0, s28
	s_nop 0
	global_load_lds_dwordx4 v[218:219], off
	v_lshl_add_u64 v[218:219], v[224:225], 0, s[6:7]
	s_mov_b32 m0, s29
	s_nop 0
	global_load_lds_dwordx4 v[218:219], off
	s_waitcnt vmcnt(8)
	s_waitcnt lgkmcnt(0)
	s_barrier
	s_setprio 1
	s_waitcnt lgkmcnt(0)
	v_mfma_f32_16x16x32_bf16 v[60:63], v[146:149], v[178:181], v[60:63]
	v_mfma_f32_16x16x32_bf16 v[56:59], v[154:157], v[178:181], v[56:59]
	v_mfma_f32_16x16x32_bf16 v[44:47], v[146:149], v[188:191], v[44:47]
	v_mfma_f32_16x16x32_bf16 v[40:43], v[154:157], v[188:191], v[40:43]
	v_mfma_f32_16x16x32_bf16 v[28:31], v[146:149], v[200:203], v[28:31]
	v_mfma_f32_16x16x32_bf16 v[24:27], v[154:157], v[200:203], v[24:27]
	v_mfma_f32_16x16x32_bf16 v[12:15], v[146:149], v[210:213], v[12:15]
	v_mfma_f32_16x16x32_bf16 v[8:11], v[154:157], v[210:213], v[8:11]
	v_mfma_f32_16x16x32_bf16 v[60:63], v[150:153], v[184:187], v[60:63]
	v_mfma_f32_16x16x32_bf16 v[56:59], v[158:161], v[184:187], v[56:59]
	v_mfma_f32_16x16x32_bf16 v[44:47], v[150:153], v[194:197], v[44:47]
	v_mfma_f32_16x16x32_bf16 v[40:43], v[158:161], v[194:197], v[40:43]
	v_mfma_f32_16x16x32_bf16 v[28:31], v[150:153], v[206:209], v[28:31]
	v_mfma_f32_16x16x32_bf16 v[24:27], v[158:161], v[206:209], v[24:27]
	v_mfma_f32_16x16x32_bf16 v[12:15], v[150:153], v[214:217], v[12:15]
	v_mfma_f32_16x16x32_bf16 v[8:11], v[158:161], v[214:217], v[8:11]
	s_setprio 0
	s_setprio 1
	v_mfma_f32_16x16x32_bf16 v[52:55], v[162:165], v[178:181], v[52:55]
	v_mfma_f32_16x16x32_bf16 v[48:51], v[170:173], v[178:181], v[48:51]
	v_mfma_f32_16x16x32_bf16 v[36:39], v[162:165], v[188:191], v[36:39]
	v_mfma_f32_16x16x32_bf16 v[32:35], v[170:173], v[188:191], v[32:35]
	v_mfma_f32_16x16x32_bf16 v[20:23], v[162:165], v[200:203], v[20:23]
	v_mfma_f32_16x16x32_bf16 v[16:19], v[170:173], v[200:203], v[16:19]
	v_mfma_f32_16x16x32_bf16 v[4:7], v[162:165], v[210:213], v[4:7]
	v_mfma_f32_16x16x32_bf16 v[0:3], v[170:173], v[210:213], v[0:3]
	v_mfma_f32_16x16x32_bf16 v[52:55], v[166:169], v[184:187], v[52:55]
	v_mfma_f32_16x16x32_bf16 v[48:51], v[174:177], v[184:187], v[48:51]
	v_mfma_f32_16x16x32_bf16 v[36:39], v[166:169], v[194:197], v[36:39]
	v_mfma_f32_16x16x32_bf16 v[32:35], v[174:177], v[194:197], v[32:35]
	v_mfma_f32_16x16x32_bf16 v[20:23], v[166:169], v[206:209], v[20:23]
	v_mfma_f32_16x16x32_bf16 v[16:19], v[174:177], v[206:209], v[16:19]
	v_mfma_f32_16x16x32_bf16 v[4:7], v[166:169], v[214:217], v[4:7]
	v_mfma_f32_16x16x32_bf16 v[0:3], v[174:177], v[214:217], v[0:3]
	s_setprio 0
	s_barrier
	s_add_i32 s30, s30, 2
	s_add_u32 s12, s12, 0x100
	s_addc_u32 s13, s13, 0
	s_cmp_gt_u32 s30, 61

.LBB0_952:
	v_bfe_u32 v199, v226, 4, 2
	s_lshl_b32 s6, s6, 5
	v_lshlrev_b32_e32 v11, 6, v226
	v_and_b32_e32 v191, 15, v226
	v_lshlrev_b32_e32 v9, 4, v199
	s_and_b32 s19, s6, 0x60
	v_and_b32_e32 v197, 0x3c0, v11
	v_lshl_or_b32 v132, s7, 6, v191
	v_lshl_or_b32 v10, v191, 6, v9
	s_lshl_b32 s7, s7, 13
	v_and_b32_e32 v196, 32, v160
	v_or_b32_e32 v9, v9, v197
	s_lshl_b32 s6, s19, 7
	v_bitop3_b32 v10, v10, s7, v196 bitop3:0xde
	v_bitop3_b32 v9, s6, v9, v196 bitop3:0xf6
	s_mov_b64 s[6:7], 0x80
	s_add_i32 m0, s15, 0x18000
	v_lshl_add_u64 v[6:7], v[6:7], 0, s[6:7]
	s_waitcnt vmcnt(2)
	s_barrier
	global_load_lds_dwordx4 v[6:7], off
	v_lshl_add_u64 v[4:5], v[4:5], 0, s[6:7]
	s_add_i32 m0, s15, 0x1a000
	s_add_i32 s20, s15, 0x8000
	s_add_i32 s21, s15, 0xa000
	global_load_lds_dwordx4 v[4:5], off
	v_lshl_add_u64 v[2:3], v[2:3], 0, s[6:7]
	s_mov_b32 m0, s20
	s_add_u32 s22, s0, 0x40080
	global_load_lds_dwordx4 v[2:3], off
	v_lshl_add_u64 v[0:1], v[0:1], 0, s[6:7]
	s_mov_b32 m0, s21
	s_addc_u32 s23, s1, 0
	global_load_lds_dwordx4 v[0:1], off
	s_add_i32 m0, s15, 0x1c000
	v_lshl_add_u64 v[0:1], s[22:23], 0, v[156:157]
	global_load_lds_dwordx4 v[0:1], off
	v_lshl_add_u64 v[0:1], s[22:23], 0, v[152:153]
	s_add_i32 m0, s15, 0x1e000
	s_lshl_b32 s10, s41, 4
	global_load_lds_dwordx4 v[0:1], off
	s_lshl_b32 s13, s53, 1
	v_lshrrev_b32_e32 v192, 7, v226
	v_readlane_b32 s24, v254, 0
	s_or_b32 s10, s10, s13
	v_lshlrev_b32_e32 v0, 15, v192
	v_lshlrev_b32_e32 v1, 11, v185
	v_readlane_b32 s26, v254, 2
	v_readlane_b32 s27, v254, 3
	s_lshl_b64 s[10:11], s[10:11], 19
	v_or3_b32 v0, v183, v0, v1
	s_mov_b64 s[22:23], s[26:27]
	v_lshrrev_b32_e32 v193, 11, v8
	v_add_u32_e32 v160, v0, v184
	s_add_u32 s10, s22, s10
	v_lshlrev_b32_e32 v0, 15, v193
	s_waitcnt vmcnt(6)
	v_readlane_b32 s25, v254, 1
	s_addc_u32 s11, s23, s11
	v_or3_b32 v0, v183, v0, v1
	s_add_i32 s48, 0, 0x10000
	s_add_i32 s49, 0, 0x14000
	s_add_i32 s51, 0, 0x18000
	s_add_i32 s53, 0, 0x1c000
	v_mov_b32_e32 v161, v157
	v_add_u32_e32 v162, v0, v184
	v_mov_b32_e32 v163, v157
	s_add_i32 s25, s48, s12
	s_add_i32 s27, s49, s12
	s_add_i32 s29, s51, s12
	s_add_i32 s31, s53, s12
	s_mov_b64 s[8:9], 0x40080
	v_lshl_add_u64 v[128:129], s[10:11], 0, v[160:161]
	v_lshl_add_u64 v[130:131], s[10:11], 0, v[162:163]
	s_mov_b32 s22, -2
	v_add_u32_e32 v133, s48, v9
	v_add_u32_e32 v134, s49, v9
	v_add_u32_e32 v135, 0, v10
	s_add_i32 s23, s15, 0xc000
	s_add_i32 s24, s15, 0xe000
	s_add_i32 s26, s25, 0x2000
	s_add_i32 s28, s27, 0x2000
	v_add_u32_e32 v136, s51, v9
	v_add_u32_e32 v137, s53, v9
	s_add_i32 s30, s29, 0x2000
	s_add_i32 s34, s31, 0x2000
	s_barrier
	ds_read_b128 v[138:141], v133
	ds_read_b128 v[142:145], v133 offset:1024
	ds_read_b128 v[146:149], v133 offset:2048
	ds_read_b128 v[164:167], v133 offset:3072
	ds_read_b128 v[168:171], v134
	ds_read_b128 v[172:175], v134 offset:1024
	ds_read_b128 v[176:179], v134 offset:2048
	ds_read_b128 v[200:203], v134 offset:3072
	s_add_u32 s10, s8, 0xfffc0080
	s_addc_u32 s11, s9, -1
	s_cmp_lg_u32 s22, 12
	s_cselect_b32 s10, s10, 0
	s_cselect_b32 s11, s11, 0
	s_add_u32 s12, s4, s10
	s_addc_u32 s13, s5, s11
	s_add_u32 s10, s0, s10
	s_addc_u32 s11, s1, s11
	s_mov_b32 m0, s23
	v_lshl_add_u64 v[150:151], v[128:129], 0, s[8:9]
	ds_read_b128 v[204:207], v135
	ds_read_b128 v[208:211], v135 offset:1024
	ds_read_b128 v[212:215], v135 offset:2048
	ds_read_b128 v[216:219], v135 offset:3072
	ds_read_b128 v[220:223], v135 offset:4096
	ds_read_b128 v[228:231], v135 offset:5120
	ds_read_b128 v[232:235], v135 offset:6144
	ds_read_b128 v[236:239], v135 offset:7168
	global_load_lds_dwordx4 v[150:151], off
	v_lshl_add_u64 v[150:151], v[130:131], 0, s[8:9]
	s_mov_b32 m0, s24
	s_nop 0
	global_load_lds_dwordx4 v[150:151], off
	s_waitcnt vmcnt(8)
	s_waitcnt lgkmcnt(0)
	s_barrier
	s_setprio 1
	s_waitcnt lgkmcnt(0)
	v_mfma_f32_16x16x32_bf16 v[124:127], v[138:141], v[204:207], 0
	v_mfma_f32_16x16x32_bf16 v[120:123], v[146:149], v[204:207], 0
	v_mfma_f32_16x16x32_bf16 v[108:111], v[138:141], v[212:215], 0
	v_mfma_f32_16x16x32_bf16 v[104:107], v[146:149], v[212:215], 0
	v_mfma_f32_16x16x32_bf16 v[92:95], v[138:141], v[220:223], 0
	v_mfma_f32_16x16x32_bf16 v[88:91], v[146:149], v[220:223], 0
	v_mfma_f32_16x16x32_bf16 v[76:79], v[138:141], v[232:235], 0
	v_mfma_f32_16x16x32_bf16 v[72:75], v[146:149], v[232:235], 0
	v_mfma_f32_16x16x32_bf16 v[124:127], v[142:145], v[208:211], v[124:127]
	v_mfma_f32_16x16x32_bf16 v[120:123], v[164:167], v[208:211], v[120:123]
	v_mfma_f32_16x16x32_bf16 v[108:111], v[142:145], v[216:219], v[108:111]
	v_mfma_f32_16x16x32_bf16 v[104:107], v[164:167], v[216:219], v[104:107]
	v_mfma_f32_16x16x32_bf16 v[92:95], v[142:145], v[228:231], v[92:95]
	v_mfma_f32_16x16x32_bf16 v[88:91], v[164:167], v[228:231], v[88:91]
	v_mfma_f32_16x16x32_bf16 v[76:79], v[142:145], v[236:239], v[76:79]
	v_mfma_f32_16x16x32_bf16 v[72:75], v[164:167], v[236:239], v[72:75]
	s_setprio 0
	s_setprio 1
	v_mfma_f32_16x16x32_bf16 v[116:119], v[168:171], v[204:207], 0
	v_mfma_f32_16x16x32_bf16 v[112:115], v[176:179], v[204:207], 0
	v_mfma_f32_16x16x32_bf16 v[100:103], v[168:171], v[212:215], 0
	v_mfma_f32_16x16x32_bf16 v[96:99], v[176:179], v[212:215], 0
	v_mfma_f32_16x16x32_bf16 v[84:87], v[168:171], v[220:223], 0
	v_mfma_f32_16x16x32_bf16 v[80:83], v[176:179], v[220:223], 0
	v_mfma_f32_16x16x32_bf16 v[68:71], v[168:171], v[232:235], 0
	v_mfma_f32_16x16x32_bf16 v[64:67], v[176:179], v[232:235], 0
	v_mfma_f32_16x16x32_bf16 v[116:119], v[172:175], v[208:211], v[116:119]
	v_mfma_f32_16x16x32_bf16 v[112:115], v[200:203], v[208:211], v[112:115]
	v_mfma_f32_16x16x32_bf16 v[100:103], v[172:175], v[216:219], v[100:103]
	v_mfma_f32_16x16x32_bf16 v[96:99], v[200:203], v[216:219], v[96:99]
	v_mfma_f32_16x16x32_bf16 v[84:87], v[172:175], v[228:231], v[84:87]
	v_mfma_f32_16x16x32_bf16 v[80:83], v[200:203], v[228:231], v[80:83]
	v_mfma_f32_16x16x32_bf16 v[68:71], v[172:175], v[236:239], v[68:71]
	v_mfma_f32_16x16x32_bf16 v[64:67], v[200:203], v[236:239], v[64:67]
	s_setprio 0
	s_barrier
	s_mov_b32 m0, s25
	v_lshl_add_u64 v[150:151], s[10:11], 0, v[156:157]
	s_add_u32 s36, s10, 0x40000
	ds_read_b128 v[204:207], v135 offset:16384
	ds_read_b128 v[208:211], v135 offset:17408
	ds_read_b128 v[212:215], v135 offset:18432
	ds_read_b128 v[216:219], v135 offset:19456
	ds_read_b128 v[220:223], v135 offset:20480
	ds_read_b128 v[228:231], v135 offset:21504
	ds_read_b128 v[232:235], v135 offset:22528
	ds_read_b128 v[236:239], v135 offset:23552
	global_load_lds_dwordx4 v[150:151], off
	v_lshl_add_u64 v[180:181], s[10:11], 0, v[152:153]
	s_mov_b32 m0, s26
	s_addc_u32 s37, s11, 0
	global_load_lds_dwordx4 v[180:181], off
	v_lshl_add_u64 v[224:225], s[36:37], 0, v[156:157]
	s_mov_b32 m0, s27
	v_lshl_add_u64 v[240:241], s[12:13], 0, v[154:155]
	global_load_lds_dwordx4 v[224:225], off
	v_lshl_add_u64 v[224:225], s[36:37], 0, v[152:153]
	s_mov_b32 m0, s28
	s_nop 0
	global_load_lds_dwordx4 v[224:225], off
	v_lshl_add_u64 v[224:225], s[12:13], 0, v[158:159]
	s_mov_b32 m0, s15
	s_nop 0
	global_load_lds_dwordx4 v[224:225], off
	s_mov_b32 m0, s16
	s_nop 0
	global_load_lds_dwordx4 v[240:241], off
	s_waitcnt vmcnt(8)
	s_waitcnt lgkmcnt(0)
	s_barrier
	s_setprio 1
	s_waitcnt lgkmcnt(0)
	v_mfma_f32_16x16x32_bf16 v[60:63], v[138:141], v[204:207], 0
	v_mfma_f32_16x16x32_bf16 v[56:59], v[146:149], v[204:207], 0
	v_mfma_f32_16x16x32_bf16 v[44:47], v[138:141], v[212:215], 0
	v_mfma_f32_16x16x32_bf16 v[40:43], v[146:149], v[212:215], 0
	v_mfma_f32_16x16x32_bf16 v[28:31], v[138:141], v[220:223], 0
	v_mfma_f32_16x16x32_bf16 v[24:27], v[146:149], v[220:223], 0
	v_mfma_f32_16x16x32_bf16 v[12:15], v[138:141], v[232:235], 0
	v_mfma_f32_16x16x32_bf16 v[8:11], v[146:149], v[232:235], 0
	v_mfma_f32_16x16x32_bf16 v[60:63], v[142:145], v[208:211], v[60:63]
	v_mfma_f32_16x16x32_bf16 v[56:59], v[164:167], v[208:211], v[56:59]
	v_mfma_f32_16x16x32_bf16 v[44:47], v[142:145], v[216:219], v[44:47]
	v_mfma_f32_16x16x32_bf16 v[40:43], v[164:167], v[216:219], v[40:43]
	v_mfma_f32_16x16x32_bf16 v[28:31], v[142:145], v[228:231], v[28:31]
	v_mfma_f32_16x16x32_bf16 v[24:27], v[164:167], v[228:231], v[24:27]
	v_mfma_f32_16x16x32_bf16 v[12:15], v[142:145], v[236:239], v[12:15]
	v_mfma_f32_16x16x32_bf16 v[8:11], v[164:167], v[236:239], v[8:11]
	s_setprio 0
	s_setprio 1
	v_mfma_f32_16x16x32_bf16 v[52:55], v[168:171], v[204:207], 0
	v_mfma_f32_16x16x32_bf16 v[48:51], v[176:179], v[204:207], 0
	v_mfma_f32_16x16x32_bf16 v[36:39], v[168:171], v[212:215], 0
	v_mfma_f32_16x16x32_bf16 v[32:35], v[176:179], v[212:215], 0
	v_mfma_f32_16x16x32_bf16 v[20:23], v[168:171], v[220:223], 0
	v_mfma_f32_16x16x32_bf16 v[16:19], v[176:179], v[220:223], 0
	v_mfma_f32_16x16x32_bf16 v[4:7], v[168:171], v[232:235], 0
	v_mfma_f32_16x16x32_bf16 v[0:3], v[176:179], v[232:235], 0
	v_mfma_f32_16x16x32_bf16 v[52:55], v[172:175], v[208:211], v[52:55]
	v_mfma_f32_16x16x32_bf16 v[48:51], v[200:203], v[208:211], v[48:51]
	v_mfma_f32_16x16x32_bf16 v[36:39], v[172:175], v[216:219], v[36:39]
	v_mfma_f32_16x16x32_bf16 v[32:35], v[200:203], v[216:219], v[32:35]
	v_mfma_f32_16x16x32_bf16 v[20:23], v[172:175], v[228:231], v[20:23]
	v_mfma_f32_16x16x32_bf16 v[16:19], v[200:203], v[228:231], v[16:19]
	v_mfma_f32_16x16x32_bf16 v[4:7], v[172:175], v[236:239], v[4:7]
	v_mfma_f32_16x16x32_bf16 v[0:3], v[200:203], v[236:239], v[0:3]
	s_setprio 0
	s_barrier
	ds_read_b128 v[138:141], v136
	ds_read_b128 v[142:145], v136 offset:1024
	ds_read_b128 v[146:149], v136 offset:2048
	ds_read_b128 v[164:167], v136 offset:3072
	ds_read_b128 v[168:171], v137
	ds_read_b128 v[172:175], v137 offset:1024
	ds_read_b128 v[176:179], v137 offset:2048
	ds_read_b128 v[200:203], v137 offset:3072
	s_add_u32 s12, s12, 0x40000
	s_addc_u32 s13, s13, 0
	s_mov_b32 m0, s17
	v_lshl_add_u64 v[242:243], s[12:13], 0, v[158:159]
	ds_read_b128 v[204:207], v135 offset:32768
	ds_read_b128 v[208:211], v135 offset:33792
	ds_read_b128 v[212:215], v135 offset:34816
	ds_read_b128 v[216:219], v135 offset:35840
	ds_read_b128 v[220:223], v135 offset:36864
	ds_read_b128 v[228:231], v135 offset:37888
	ds_read_b128 v[232:235], v135 offset:38912
	ds_read_b128 v[236:239], v135 offset:39936
	global_load_lds_dwordx4 v[242:243], off
	v_lshl_add_u64 v[242:243], s[12:13], 0, v[154:155]
	s_mov_b32 m0, s18
	s_nop 0
	global_load_lds_dwordx4 v[242:243], off
	s_waitcnt vmcnt(8)
	s_waitcnt lgkmcnt(0)
	s_barrier
	s_setprio 1
	s_waitcnt lgkmcnt(0)
	v_mfma_f32_16x16x32_bf16 v[124:127], v[138:141], v[204:207], v[124:127]
	v_mfma_f32_16x16x32_bf16 v[120:123], v[146:149], v[204:207], v[120:123]
	v_mfma_f32_16x16x32_bf16 v[108:111], v[138:141], v[212:215], v[108:111]
	v_mfma_f32_16x16x32_bf16 v[104:107], v[146:149], v[212:215], v[104:107]
	v_mfma_f32_16x16x32_bf16 v[92:95], v[138:141], v[220:223], v[92:95]
	v_mfma_f32_16x16x32_bf16 v[88:91], v[146:149], v[220:223], v[88:91]
	v_mfma_f32_16x16x32_bf16 v[76:79], v[138:141], v[232:235], v[76:79]
	v_mfma_f32_16x16x32_bf16 v[72:75], v[146:149], v[232:235], v[72:75]
	v_mfma_f32_16x16x32_bf16 v[124:127], v[142:145], v[208:211], v[124:127]
	v_mfma_f32_16x16x32_bf16 v[120:123], v[164:167], v[208:211], v[120:123]
	v_mfma_f32_16x16x32_bf16 v[108:111], v[142:145], v[216:219], v[108:111]
	v_mfma_f32_16x16x32_bf16 v[104:107], v[164:167], v[216:219], v[104:107]
	v_mfma_f32_16x16x32_bf16 v[92:95], v[142:145], v[228:231], v[92:95]
	v_mfma_f32_16x16x32_bf16 v[88:91], v[164:167], v[228:231], v[88:91]
	v_mfma_f32_16x16x32_bf16 v[76:79], v[142:145], v[236:239], v[76:79]
	v_mfma_f32_16x16x32_bf16 v[72:75], v[164:167], v[236:239], v[72:75]
	s_setprio 0
	s_setprio 1
	v_mfma_f32_16x16x32_bf16 v[116:119], v[168:171], v[204:207], v[116:119]
	v_mfma_f32_16x16x32_bf16 v[112:115], v[176:179], v[204:207], v[112:115]
	v_mfma_f32_16x16x32_bf16 v[100:103], v[168:171], v[212:215], v[100:103]
	v_mfma_f32_16x16x32_bf16 v[96:99], v[176:179], v[212:215], v[96:99]
	v_mfma_f32_16x16x32_bf16 v[84:87], v[168:171], v[220:223], v[84:87]
	v_mfma_f32_16x16x32_bf16 v[80:83], v[176:179], v[220:223], v[80:83]
	v_mfma_f32_16x16x32_bf16 v[68:71], v[168:171], v[232:235], v[68:71]
	v_mfma_f32_16x16x32_bf16 v[64:67], v[176:179], v[232:235], v[64:67]
	v_mfma_f32_16x16x32_bf16 v[116:119], v[172:175], v[208:211], v[116:119]
	v_mfma_f32_16x16x32_bf16 v[112:115], v[200:203], v[208:211], v[112:115]
	v_mfma_f32_16x16x32_bf16 v[100:103], v[172:175], v[216:219], v[100:103]
	v_mfma_f32_16x16x32_bf16 v[96:99], v[200:203], v[216:219], v[96:99]
	v_mfma_f32_16x16x32_bf16 v[84:87], v[172:175], v[228:231], v[84:87]
	v_mfma_f32_16x16x32_bf16 v[80:83], v[200:203], v[228:231], v[80:83]
	v_mfma_f32_16x16x32_bf16 v[68:71], v[172:175], v[236:239], v[68:71]
	v_mfma_f32_16x16x32_bf16 v[64:67], v[200:203], v[236:239], v[64:67]
	s_setprio 0
	s_barrier
	s_mov_b32 m0, s29
	v_lshl_add_u64 v[150:151], v[150:151], 0, s[6:7]
	s_add_u32 s10, s10, 0x40080
	ds_read_b128 v[204:207], v135 offset:49152
	ds_read_b128 v[208:211], v135 offset:50176
	ds_read_b128 v[212:215], v135 offset:51200
	ds_read_b128 v[216:219], v135 offset:52224
	ds_read_b128 v[220:223], v135 offset:53248
	ds_read_b128 v[228:231], v135 offset:54272
	ds_read_b128 v[232:235], v135 offset:55296
	ds_read_b128 v[236:239], v135 offset:56320
	global_load_lds_dwordx4 v[150:151], off
	v_lshl_add_u64 v[150:151], v[180:181], 0, s[6:7]
	s_mov_b32 m0, s30
	s_addc_u32 s11, s11, 0
	global_load_lds_dwordx4 v[150:151], off
	v_lshl_add_u64 v[150:151], s[10:11], 0, v[156:157]
	s_mov_b32 m0, s31
	s_nop 0
	global_load_lds_dwordx4 v[150:151], off
	v_lshl_add_u64 v[150:151], s[10:11], 0, v[152:153]
	s_mov_b32 m0, s34
	s_nop 0
	global_load_lds_dwordx4 v[150:151], off
	v_lshl_add_u64 v[150:151], v[224:225], 0, s[6:7]
	s_mov_b32 m0, s20
	s_nop 0
	global_load_lds_dwordx4 v[150:151], off
	v_lshl_add_u64 v[150:151], v[240:241], 0, s[6:7]
	s_mov_b32 m0, s21
	s_nop 0
	global_load_lds_dwordx4 v[150:151], off
	s_waitcnt vmcnt(8)
	s_waitcnt lgkmcnt(0)
	s_barrier
	s_setprio 1
	s_waitcnt lgkmcnt(0)
	v_mfma_f32_16x16x32_bf16 v[60:63], v[138:141], v[204:207], v[60:63]
	v_mfma_f32_16x16x32_bf16 v[56:59], v[146:149], v[204:207], v[56:59]
	v_mfma_f32_16x16x32_bf16 v[44:47], v[138:141], v[212:215], v[44:47]
	v_mfma_f32_16x16x32_bf16 v[40:43], v[146:149], v[212:215], v[40:43]
	v_mfma_f32_16x16x32_bf16 v[28:31], v[138:141], v[220:223], v[28:31]
	v_mfma_f32_16x16x32_bf16 v[24:27], v[146:149], v[220:223], v[24:27]
	v_mfma_f32_16x16x32_bf16 v[12:15], v[138:141], v[232:235], v[12:15]
	v_mfma_f32_16x16x32_bf16 v[8:11], v[146:149], v[232:235], v[8:11]
	v_mfma_f32_16x16x32_bf16 v[60:63], v[142:145], v[208:211], v[60:63]
	v_mfma_f32_16x16x32_bf16 v[56:59], v[164:167], v[208:211], v[56:59]
	v_mfma_f32_16x16x32_bf16 v[44:47], v[142:145], v[216:219], v[44:47]
	v_mfma_f32_16x16x32_bf16 v[40:43], v[164:167], v[216:219], v[40:43]
	v_mfma_f32_16x16x32_bf16 v[28:31], v[142:145], v[228:231], v[28:31]
	v_mfma_f32_16x16x32_bf16 v[24:27], v[164:167], v[228:231], v[24:27]
	v_mfma_f32_16x16x32_bf16 v[12:15], v[142:145], v[236:239], v[12:15]
	v_mfma_f32_16x16x32_bf16 v[8:11], v[164:167], v[236:239], v[8:11]
	s_setprio 0
	s_setprio 1
	v_mfma_f32_16x16x32_bf16 v[52:55], v[168:171], v[204:207], v[52:55]
	v_mfma_f32_16x16x32_bf16 v[48:51], v[176:179], v[204:207], v[48:51]
	v_mfma_f32_16x16x32_bf16 v[36:39], v[168:171], v[212:215], v[36:39]
	v_mfma_f32_16x16x32_bf16 v[32:35], v[176:179], v[212:215], v[32:35]
	v_mfma_f32_16x16x32_bf16 v[20:23], v[168:171], v[220:223], v[20:23]
	v_mfma_f32_16x16x32_bf16 v[16:19], v[176:179], v[220:223], v[16:19]
	v_mfma_f32_16x16x32_bf16 v[4:7], v[168:171], v[232:235], v[4:7]
	v_mfma_f32_16x16x32_bf16 v[0:3], v[176:179], v[232:235], v[0:3]
	v_mfma_f32_16x16x32_bf16 v[52:55], v[172:175], v[208:211], v[52:55]
	v_mfma_f32_16x16x32_bf16 v[48:51], v[200:203], v[208:211], v[48:51]
	v_mfma_f32_16x16x32_bf16 v[36:39], v[172:175], v[216:219], v[36:39]
	v_mfma_f32_16x16x32_bf16 v[32:35], v[200:203], v[216:219], v[32:35]
	v_mfma_f32_16x16x32_bf16 v[20:23], v[172:175], v[228:231], v[20:23]
	v_mfma_f32_16x16x32_bf16 v[16:19], v[200:203], v[228:231], v[16:19]
	v_mfma_f32_16x16x32_bf16 v[4:7], v[172:175], v[236:239], v[4:7]
	v_mfma_f32_16x16x32_bf16 v[0:3], v[200:203], v[236:239], v[0:3]
	s_setprio 0
	s_barrier
	s_add_i32 s22, s22, 2
	s_add_u32 s8, s8, 0x100
	s_addc_u32 s9, s9, 0
	s_cmp_gt_u32 s22, 13

.LBB0_1016:
	v_lshl_or_b32 v141, s5, 6, v191
	s_lshl_b32 s5, s5, 13
	s_lshl_b32 s4, s4, 5
	v_bitop3_b32 v8, v138, s5, v140 bitop3:0xde
	s_and_b32 s21, s4, 0x60
	s_mov_b64 s[4:5], 0x80
	s_add_i32 m0, s17, 0x18000
	v_lshl_add_u64 v[6:7], v[6:7], 0, s[4:5]
	s_waitcnt vmcnt(2)
	s_barrier
	global_load_lds_dwordx4 v[6:7], off
	v_lshl_add_u64 v[4:5], v[4:5], 0, s[4:5]
	s_add_i32 m0, s17, 0x1a000
	s_add_i32 s22, s17, 0x8000
	s_add_i32 s23, s17, 0xa000
	global_load_lds_dwordx4 v[4:5], off
	v_lshl_add_u64 v[2:3], v[2:3], 0, s[4:5]
	s_mov_b32 m0, s22
	s_add_u32 s10, s0, 0x100080
	global_load_lds_dwordx4 v[2:3], off
	v_lshl_add_u64 v[0:1], v[0:1], 0, s[4:5]
	s_mov_b32 m0, s23
	s_addc_u32 s11, s1, 0
	global_load_lds_dwordx4 v[0:1], off
	s_add_i32 m0, s17, 0x1c000
	v_lshl_add_u64 v[0:1], s[10:11], 0, v[132:133]
	global_load_lds_dwordx4 v[0:1], off
	v_lshl_add_u64 v[0:1], s[10:11], 0, v[128:129]
	s_add_i32 m0, s17, 0x1e000
	s_add_u32 s10, s44, 0x100080
	global_load_lds_dwordx4 v[0:1], off
	s_addc_u32 s11, s45, 0
	v_lshlrev_b32_e32 v0, 17, v192
	v_lshlrev_b32_e32 v1, 13, v185
	s_add_u32 s12, s96, s54
	v_or3_b32 v0, v183, v0, v1
	s_addc_u32 s13, s97, 0
	s_waitcnt vmcnt(6)
	v_add_u32_e32 v136, v0, v184
	v_lshlrev_b32_e32 v0, 17, v193
	s_add_u32 s24, s12, 0x2100100
	v_lshl_or_b32 v9, s21, 7, v139
	v_or3_b32 v0, v183, v0, v1
	s_addc_u32 s25, s13, 0
	s_add_i32 s29, s48, s37
	s_add_i32 s31, s49, s37
	s_add_i32 s35, s51, s37
	s_add_i32 s37, s53, s37
	v_mov_b32_e32 v137, v133
	v_add_u32_e32 v138, v0, v184
	v_mov_b32_e32 v139, v133
	s_mov_b32 s26, -2
	v_add_u32_e32 v140, s48, v9
	v_add_u32_e32 v142, s49, v9
	v_add_u32_e32 v143, 0, v8
	s_add_i32 s27, s17, 0xc000
	s_add_i32 s28, s17, 0xe000
	s_add_i32 s30, s29, 0x2000
	s_add_i32 s34, s31, 0x2000
	v_add_u32_e32 v144, s51, v9
	v_add_u32_e32 v145, s53, v9
	s_add_i32 s36, s35, 0x2000
	s_add_i32 s38, s37, 0x2000
	s_barrier
	ds_read_b128 v[146:149], v140
	ds_read_b128 v[150:153], v140 offset:1024
	ds_read_b128 v[154:157], v140 offset:2048
	ds_read_b128 v[158:161], v140 offset:3072
	ds_read_b128 v[162:165], v142
	ds_read_b128 v[166:169], v142 offset:1024
	ds_read_b128 v[170:173], v142 offset:2048
	ds_read_b128 v[174:177], v142 offset:3072
	s_add_u32 s12, s10, 0xfff00080
	s_addc_u32 s13, s11, -1
	s_cmp_eq_u32 s26, 60
	s_cselect_b32 s15, s3, s13
	s_cselect_b32 s14, s2, s12
	s_cselect_b32 s13, s1, s25
	s_cselect_b32 s12, s0, s24
	s_mov_b32 m0, s27
	v_lshl_add_u64 v[212:213], s[10:11], 0, v[136:137]
	ds_read_b128 v[178:181], v143
	ds_read_b128 v[184:187], v143 offset:1024
	ds_read_b128 v[188:191], v143 offset:2048
	ds_read_b128 v[192:195], v143 offset:3072
	ds_read_b128 v[196:199], v143 offset:4096
	ds_read_b128 v[200:203], v143 offset:5120
	ds_read_b128 v[204:207], v143 offset:6144
	ds_read_b128 v[208:211], v143 offset:7168
	global_load_lds_dwordx4 v[212:213], off
	v_lshl_add_u64 v[212:213], s[10:11], 0, v[138:139]
	s_mov_b32 m0, s28
	s_nop 0
	global_load_lds_dwordx4 v[212:213], off
	s_waitcnt vmcnt(8)
	s_waitcnt lgkmcnt(0)
	s_barrier
	s_setprio 1
	s_waitcnt lgkmcnt(0)
	v_mfma_f32_16x16x32_bf16 v[124:127], v[146:149], v[178:181], 0
	v_mfma_f32_16x16x32_bf16 v[120:123], v[154:157], v[178:181], 0
	v_mfma_f32_16x16x32_bf16 v[112:115], v[146:149], v[188:191], 0
	v_mfma_f32_16x16x32_bf16 v[104:107], v[154:157], v[188:191], 0
	v_mfma_f32_16x16x32_bf16 v[96:99], v[146:149], v[196:199], 0
	v_mfma_f32_16x16x32_bf16 v[88:91], v[154:157], v[196:199], 0
	v_mfma_f32_16x16x32_bf16 v[80:83], v[146:149], v[204:207], 0
	v_mfma_f32_16x16x32_bf16 v[72:75], v[154:157], v[204:207], 0
	v_mfma_f32_16x16x32_bf16 v[124:127], v[150:153], v[184:187], v[124:127]
	v_mfma_f32_16x16x32_bf16 v[120:123], v[158:161], v[184:187], v[120:123]
	v_mfma_f32_16x16x32_bf16 v[112:115], v[150:153], v[192:195], v[112:115]
	v_mfma_f32_16x16x32_bf16 v[104:107], v[158:161], v[192:195], v[104:107]
	v_mfma_f32_16x16x32_bf16 v[96:99], v[150:153], v[200:203], v[96:99]
	v_mfma_f32_16x16x32_bf16 v[88:91], v[158:161], v[200:203], v[88:91]
	v_mfma_f32_16x16x32_bf16 v[80:83], v[150:153], v[208:211], v[80:83]
	v_mfma_f32_16x16x32_bf16 v[72:75], v[158:161], v[208:211], v[72:75]
	s_setprio 0
	s_setprio 1
	v_mfma_f32_16x16x32_bf16 v[116:119], v[162:165], v[178:181], 0
	v_mfma_f32_16x16x32_bf16 v[108:111], v[170:173], v[178:181], 0
	v_mfma_f32_16x16x32_bf16 v[100:103], v[162:165], v[188:191], 0
	v_mfma_f32_16x16x32_bf16 v[92:95], v[170:173], v[188:191], 0
	v_mfma_f32_16x16x32_bf16 v[84:87], v[162:165], v[196:199], 0
	v_mfma_f32_16x16x32_bf16 v[76:79], v[170:173], v[196:199], 0
	v_mfma_f32_16x16x32_bf16 v[68:71], v[162:165], v[204:207], 0
	v_mfma_f32_16x16x32_bf16 v[64:67], v[170:173], v[204:207], 0
	v_mfma_f32_16x16x32_bf16 v[116:119], v[166:169], v[184:187], v[116:119]
	v_mfma_f32_16x16x32_bf16 v[108:111], v[174:177], v[184:187], v[108:111]
	v_mfma_f32_16x16x32_bf16 v[100:103], v[166:169], v[192:195], v[100:103]
	v_mfma_f32_16x16x32_bf16 v[92:95], v[174:177], v[192:195], v[92:95]
	v_mfma_f32_16x16x32_bf16 v[84:87], v[166:169], v[200:203], v[84:87]
	v_mfma_f32_16x16x32_bf16 v[76:79], v[174:177], v[200:203], v[76:79]
	v_mfma_f32_16x16x32_bf16 v[68:71], v[166:169], v[208:211], v[68:71]
	v_mfma_f32_16x16x32_bf16 v[64:67], v[174:177], v[208:211], v[64:67]
	s_setprio 0
	s_barrier
	s_mov_b32 m0, s29
	v_lshl_add_u64 v[212:213], s[12:13], 0, v[132:133]
	s_add_u32 s40, s12, 0x100000
	ds_read_b128 v[178:181], v143 offset:16384
	ds_read_b128 v[184:187], v143 offset:17408
	ds_read_b128 v[188:191], v143 offset:18432
	ds_read_b128 v[192:195], v143 offset:19456
	ds_read_b128 v[196:199], v143 offset:20480
	ds_read_b128 v[200:203], v143 offset:21504
	ds_read_b128 v[204:207], v143 offset:22528
	ds_read_b128 v[208:211], v143 offset:23552
	global_load_lds_dwordx4 v[212:213], off
	v_lshl_add_u64 v[214:215], s[12:13], 0, v[128:129]
	s_mov_b32 m0, s30
	s_addc_u32 s41, s13, 0
	global_load_lds_dwordx4 v[214:215], off
	v_lshl_add_u64 v[216:217], s[40:41], 0, v[132:133]
	s_mov_b32 m0, s31
	v_lshl_add_u64 v[218:219], s[14:15], 0, v[130:131]
	global_load_lds_dwordx4 v[216:217], off
	v_lshl_add_u64 v[216:217], s[40:41], 0, v[128:129]
	s_mov_b32 m0, s34
	s_nop 0
	global_load_lds_dwordx4 v[216:217], off
	v_lshl_add_u64 v[216:217], s[14:15], 0, v[134:135]
	s_mov_b32 m0, s17
	s_nop 0
	global_load_lds_dwordx4 v[216:217], off
	s_mov_b32 m0, s18
	s_nop 0
	global_load_lds_dwordx4 v[218:219], off
	s_waitcnt vmcnt(8)
	s_waitcnt lgkmcnt(0)
	s_barrier
	s_setprio 1
	s_waitcnt lgkmcnt(0)
	v_mfma_f32_16x16x32_bf16 v[60:63], v[146:149], v[178:181], 0
	v_mfma_f32_16x16x32_bf16 v[56:59], v[154:157], v[178:181], 0
	v_mfma_f32_16x16x32_bf16 v[48:51], v[146:149], v[188:191], 0
	v_mfma_f32_16x16x32_bf16 v[40:43], v[154:157], v[188:191], 0
	v_mfma_f32_16x16x32_bf16 v[32:35], v[146:149], v[196:199], 0
	v_mfma_f32_16x16x32_bf16 v[24:27], v[154:157], v[196:199], 0
	v_mfma_f32_16x16x32_bf16 v[16:19], v[146:149], v[204:207], 0
	v_mfma_f32_16x16x32_bf16 v[8:11], v[154:157], v[204:207], 0
	v_mfma_f32_16x16x32_bf16 v[60:63], v[150:153], v[184:187], v[60:63]
	v_mfma_f32_16x16x32_bf16 v[56:59], v[158:161], v[184:187], v[56:59]
	v_mfma_f32_16x16x32_bf16 v[48:51], v[150:153], v[192:195], v[48:51]
	v_mfma_f32_16x16x32_bf16 v[40:43], v[158:161], v[192:195], v[40:43]
	v_mfma_f32_16x16x32_bf16 v[32:35], v[150:153], v[200:203], v[32:35]
	v_mfma_f32_16x16x32_bf16 v[24:27], v[158:161], v[200:203], v[24:27]
	v_mfma_f32_16x16x32_bf16 v[16:19], v[150:153], v[208:211], v[16:19]
	v_mfma_f32_16x16x32_bf16 v[8:11], v[158:161], v[208:211], v[8:11]
	s_setprio 0
	s_setprio 1
	v_mfma_f32_16x16x32_bf16 v[52:55], v[162:165], v[178:181], 0
	v_mfma_f32_16x16x32_bf16 v[44:47], v[170:173], v[178:181], 0
	v_mfma_f32_16x16x32_bf16 v[36:39], v[162:165], v[188:191], 0
	v_mfma_f32_16x16x32_bf16 v[28:31], v[170:173], v[188:191], 0
	v_mfma_f32_16x16x32_bf16 v[20:23], v[162:165], v[196:199], 0
	v_mfma_f32_16x16x32_bf16 v[12:15], v[170:173], v[196:199], 0
	v_mfma_f32_16x16x32_bf16 v[4:7], v[162:165], v[204:207], 0
	v_mfma_f32_16x16x32_bf16 v[0:3], v[170:173], v[204:207], 0
	v_mfma_f32_16x16x32_bf16 v[52:55], v[166:169], v[184:187], v[52:55]
	v_mfma_f32_16x16x32_bf16 v[44:47], v[174:177], v[184:187], v[44:47]
	v_mfma_f32_16x16x32_bf16 v[36:39], v[166:169], v[192:195], v[36:39]
	v_mfma_f32_16x16x32_bf16 v[28:31], v[174:177], v[192:195], v[28:31]
	v_mfma_f32_16x16x32_bf16 v[20:23], v[166:169], v[200:203], v[20:23]
	v_mfma_f32_16x16x32_bf16 v[12:15], v[174:177], v[200:203], v[12:15]
	v_mfma_f32_16x16x32_bf16 v[4:7], v[166:169], v[208:211], v[4:7]
	v_mfma_f32_16x16x32_bf16 v[0:3], v[174:177], v[208:211], v[0:3]
	s_setprio 0
	s_barrier
	ds_read_b128 v[146:149], v144
	ds_read_b128 v[150:153], v144 offset:1024
	ds_read_b128 v[154:157], v144 offset:2048
	ds_read_b128 v[158:161], v144 offset:3072
	ds_read_b128 v[162:165], v145
	ds_read_b128 v[166:169], v145 offset:1024
	ds_read_b128 v[170:173], v145 offset:2048
	ds_read_b128 v[174:177], v145 offset:3072
	s_add_u32 s14, s14, 0x100000
	s_addc_u32 s15, s15, 0
	s_mov_b32 m0, s19
	v_lshl_add_u64 v[220:221], s[14:15], 0, v[134:135]
	ds_read_b128 v[178:181], v143 offset:32768
	ds_read_b128 v[184:187], v143 offset:33792
	ds_read_b128 v[188:191], v143 offset:34816
	ds_read_b128 v[192:195], v143 offset:35840
	ds_read_b128 v[196:199], v143 offset:36864
	ds_read_b128 v[200:203], v143 offset:37888
	ds_read_b128 v[204:207], v143 offset:38912
	ds_read_b128 v[208:211], v143 offset:39936
	global_load_lds_dwordx4 v[220:221], off
	v_lshl_add_u64 v[220:221], s[14:15], 0, v[130:131]
	s_mov_b32 m0, s20
	s_nop 0
	global_load_lds_dwordx4 v[220:221], off
	s_waitcnt vmcnt(8)
	s_waitcnt lgkmcnt(0)
	s_barrier
	s_setprio 1
	s_waitcnt lgkmcnt(0)
	v_mfma_f32_16x16x32_bf16 v[124:127], v[146:149], v[178:181], v[124:127]
	v_mfma_f32_16x16x32_bf16 v[120:123], v[154:157], v[178:181], v[120:123]
	v_mfma_f32_16x16x32_bf16 v[112:115], v[146:149], v[188:191], v[112:115]
	v_mfma_f32_16x16x32_bf16 v[104:107], v[154:157], v[188:191], v[104:107]
	v_mfma_f32_16x16x32_bf16 v[96:99], v[146:149], v[196:199], v[96:99]
	v_mfma_f32_16x16x32_bf16 v[88:91], v[154:157], v[196:199], v[88:91]
	v_mfma_f32_16x16x32_bf16 v[80:83], v[146:149], v[204:207], v[80:83]
	v_mfma_f32_16x16x32_bf16 v[72:75], v[154:157], v[204:207], v[72:75]
	v_mfma_f32_16x16x32_bf16 v[124:127], v[150:153], v[184:187], v[124:127]
	v_mfma_f32_16x16x32_bf16 v[120:123], v[158:161], v[184:187], v[120:123]
	v_mfma_f32_16x16x32_bf16 v[112:115], v[150:153], v[192:195], v[112:115]
	v_mfma_f32_16x16x32_bf16 v[104:107], v[158:161], v[192:195], v[104:107]
	v_mfma_f32_16x16x32_bf16 v[96:99], v[150:153], v[200:203], v[96:99]
	v_mfma_f32_16x16x32_bf16 v[88:91], v[158:161], v[200:203], v[88:91]
	v_mfma_f32_16x16x32_bf16 v[80:83], v[150:153], v[208:211], v[80:83]
	v_mfma_f32_16x16x32_bf16 v[72:75], v[158:161], v[208:211], v[72:75]
	s_setprio 0
	s_setprio 1
	v_mfma_f32_16x16x32_bf16 v[116:119], v[162:165], v[178:181], v[116:119]
	v_mfma_f32_16x16x32_bf16 v[108:111], v[170:173], v[178:181], v[108:111]
	v_mfma_f32_16x16x32_bf16 v[100:103], v[162:165], v[188:191], v[100:103]
	v_mfma_f32_16x16x32_bf16 v[92:95], v[170:173], v[188:191], v[92:95]
	v_mfma_f32_16x16x32_bf16 v[84:87], v[162:165], v[196:199], v[84:87]
	v_mfma_f32_16x16x32_bf16 v[76:79], v[170:173], v[196:199], v[76:79]
	v_mfma_f32_16x16x32_bf16 v[68:71], v[162:165], v[204:207], v[68:71]
	v_mfma_f32_16x16x32_bf16 v[64:67], v[170:173], v[204:207], v[64:67]
	v_mfma_f32_16x16x32_bf16 v[116:119], v[166:169], v[184:187], v[116:119]
	v_mfma_f32_16x16x32_bf16 v[108:111], v[174:177], v[184:187], v[108:111]
	v_mfma_f32_16x16x32_bf16 v[100:103], v[166:169], v[192:195], v[100:103]
	v_mfma_f32_16x16x32_bf16 v[92:95], v[174:177], v[192:195], v[92:95]
	v_mfma_f32_16x16x32_bf16 v[84:87], v[166:169], v[200:203], v[84:87]
	v_mfma_f32_16x16x32_bf16 v[76:79], v[174:177], v[200:203], v[76:79]
	v_mfma_f32_16x16x32_bf16 v[68:71], v[166:169], v[208:211], v[68:71]
	v_mfma_f32_16x16x32_bf16 v[64:67], v[174:177], v[208:211], v[64:67]
	s_setprio 0
	s_barrier
	s_mov_b32 m0, s35
	v_lshl_add_u64 v[212:213], v[212:213], 0, s[4:5]
	s_add_u32 s12, s12, 0x100080
	ds_read_b128 v[178:181], v143 offset:49152
	ds_read_b128 v[184:187], v143 offset:50176
	ds_read_b128 v[188:191], v143 offset:51200
	ds_read_b128 v[192:195], v143 offset:52224
	ds_read_b128 v[196:199], v143 offset:53248
	ds_read_b128 v[200:203], v143 offset:54272
	ds_read_b128 v[204:207], v143 offset:55296
	ds_read_b128 v[208:211], v143 offset:56320
	global_load_lds_dwordx4 v[212:213], off
	v_lshl_add_u64 v[212:213], v[214:215], 0, s[4:5]
	s_mov_b32 m0, s36
	s_addc_u32 s13, s13, 0
	global_load_lds_dwordx4 v[212:213], off
	v_lshl_add_u64 v[212:213], s[12:13], 0, v[132:133]
	s_mov_b32 m0, s37
	s_nop 0
	global_load_lds_dwordx4 v[212:213], off
	v_lshl_add_u64 v[212:213], s[12:13], 0, v[128:129]
	s_mov_b32 m0, s38
	s_nop 0
	global_load_lds_dwordx4 v[212:213], off
	v_lshl_add_u64 v[212:213], v[216:217], 0, s[4:5]
	s_mov_b32 m0, s22
	s_nop 0
	global_load_lds_dwordx4 v[212:213], off
	v_lshl_add_u64 v[212:213], v[218:219], 0, s[4:5]
	s_mov_b32 m0, s23
	s_nop 0
	global_load_lds_dwordx4 v[212:213], off
	s_waitcnt vmcnt(8)
	s_waitcnt lgkmcnt(0)
	s_barrier
	s_setprio 1
	s_waitcnt lgkmcnt(0)
	v_mfma_f32_16x16x32_bf16 v[60:63], v[146:149], v[178:181], v[60:63]
	v_mfma_f32_16x16x32_bf16 v[56:59], v[154:157], v[178:181], v[56:59]
	v_mfma_f32_16x16x32_bf16 v[48:51], v[146:149], v[188:191], v[48:51]
	v_mfma_f32_16x16x32_bf16 v[40:43], v[154:157], v[188:191], v[40:43]
	v_mfma_f32_16x16x32_bf16 v[32:35], v[146:149], v[196:199], v[32:35]
	v_mfma_f32_16x16x32_bf16 v[24:27], v[154:157], v[196:199], v[24:27]
	v_mfma_f32_16x16x32_bf16 v[16:19], v[146:149], v[204:207], v[16:19]
	v_mfma_f32_16x16x32_bf16 v[8:11], v[154:157], v[204:207], v[8:11]
	v_mfma_f32_16x16x32_bf16 v[60:63], v[150:153], v[184:187], v[60:63]
	v_mfma_f32_16x16x32_bf16 v[56:59], v[158:161], v[184:187], v[56:59]
	v_mfma_f32_16x16x32_bf16 v[48:51], v[150:153], v[192:195], v[48:51]
	v_mfma_f32_16x16x32_bf16 v[40:43], v[158:161], v[192:195], v[40:43]
	v_mfma_f32_16x16x32_bf16 v[32:35], v[150:153], v[200:203], v[32:35]
	v_mfma_f32_16x16x32_bf16 v[24:27], v[158:161], v[200:203], v[24:27]
	v_mfma_f32_16x16x32_bf16 v[16:19], v[150:153], v[208:211], v[16:19]
	v_mfma_f32_16x16x32_bf16 v[8:11], v[158:161], v[208:211], v[8:11]
	s_setprio 0
	s_setprio 1
	v_mfma_f32_16x16x32_bf16 v[52:55], v[162:165], v[178:181], v[52:55]
	v_mfma_f32_16x16x32_bf16 v[44:47], v[170:173], v[178:181], v[44:47]
	v_mfma_f32_16x16x32_bf16 v[36:39], v[162:165], v[188:191], v[36:39]
	v_mfma_f32_16x16x32_bf16 v[28:31], v[170:173], v[188:191], v[28:31]
	v_mfma_f32_16x16x32_bf16 v[20:23], v[162:165], v[196:199], v[20:23]
	v_mfma_f32_16x16x32_bf16 v[12:15], v[170:173], v[196:199], v[12:15]
	v_mfma_f32_16x16x32_bf16 v[4:7], v[162:165], v[204:207], v[4:7]
	v_mfma_f32_16x16x32_bf16 v[0:3], v[170:173], v[204:207], v[0:3]
	v_mfma_f32_16x16x32_bf16 v[52:55], v[166:169], v[184:187], v[52:55]
	v_mfma_f32_16x16x32_bf16 v[44:47], v[174:177], v[184:187], v[44:47]
	v_mfma_f32_16x16x32_bf16 v[36:39], v[166:169], v[192:195], v[36:39]
	v_mfma_f32_16x16x32_bf16 v[28:31], v[174:177], v[192:195], v[28:31]
	v_mfma_f32_16x16x32_bf16 v[20:23], v[166:169], v[200:203], v[20:23]
	v_mfma_f32_16x16x32_bf16 v[12:15], v[174:177], v[200:203], v[12:15]
	v_mfma_f32_16x16x32_bf16 v[4:7], v[166:169], v[208:211], v[4:7]
	v_mfma_f32_16x16x32_bf16 v[0:3], v[174:177], v[208:211], v[0:3]
	s_setprio 0
	s_barrier
	s_add_i32 s26, s26, 2
	s_add_u32 s10, s10, 0x100
	s_addc_u32 s11, s11, 0
	s_add_u32 s24, s24, 0x100
	s_addc_u32 s25, s25, 0
	s_cmp_gt_u32 s26, 61
